# prologue EVIN/ODIN weight transposes: the 8 per-row k-scale loads issued together (one wait instead of 8 serialized round trips per item)
# speedup vs baseline: 1.0071x; 1.0071x over previous
; __device__ __forceinline__ unsigned pk_bf16(float lo, float hi) { f32x2e v = {lo, hi}; bf16x2e b = __builtin_convertvector(v, bf16x2e); return __builtin_bit_cast(unsigned, b); }
; #define LAS __attribute__((address_space(3)))
; __device__ __forceinline__ void tr_item(const float* W, int Ksrc, int N, int k0, int n0, bf16* dst, int ldt, int drow0, int dcol0, LAS float* scr, int lane, const float* nscale = nullptr, const float* kscale = nullptr) {
;     f32x4 tv[8]; const int kr_ = lane >> 3, nq_ = lane & 7;
; #pragma unroll
;     for (int i = 0; i < 8; ++i) { const int kk = 8 * i + kr_; const int kr = (k0 + kk < Ksrc) ? (k0 + kk) : (Ksrc - 1); tv[i] = __builtin_nontemporal_load((const f32x4*)(W + (size_t)kr * N + n0 + 4 * nq_)); }
; #pragma unroll
;     for (int i = 0; i < 8; ++i) { const int kk = 8 * i + kr_; const bool ok = (k0 + kk < Ksrc); LAS float* d_ = scr + kk * 33 + 4 * nq_;
;         const float ks_ = (ok && kscale) ? kscale[k0 + kk] : 1.0f;
;         d_[0] = ok ? tv[i].x * ks_ : 0.f; d_[1] = ok ? tv[i].y * ks_ : 0.f; d_[2] = ok ? tv[i].z * ks_ : 0.f; d_[3] = ok ? tv[i].w * ks_ : 0.f; }
;     asm volatile("s_waitcnt lgkmcnt(0)" ::: "memory");
;     const int c = lane & 7;
; #pragma unroll
;     for (int j = 0; j < 4; ++j) { const int n = (lane >> 3) + 8 * j; const LAS float* s = scr + (8 * c) * 33 + n;
;         const float sc = nscale ? nscale[n0 + n] : 1.0f;
;         u32x4 o; o.x = pk_bf16(s[0 * 33] * sc, s[1 * 33] * sc); o.y = pk_bf16(s[2 * 33] * sc, s[3 * 33] * sc); o.z = pk_bf16(s[4 * 33] * sc, s[5 * 33] * sc); o.w = pk_bf16(s[6 * 33] * sc, s[7 * 33] * sc);
;         *(u32x4*)(dst + (size_t)(drow0 + n) * ldt + dcol0 + k0 + 8 * c) = o; }
;     asm volatile("s_waitcnt lgkmcnt(0)" ::: "memory");
; }
; __device__ __forceinline__ void tr_matrix(const float* W, int Ksrc, int N, bf16* dst, int ldt, int dcol0, int rowmode, int drow_off, LAS float* scr, int gw, int ngw, int lane, const float* nscale = nullptr, const float* kscale = nullptr) {
;     const int nkb = (Ksrc + 63) / 64, nnb = N / 32, items = nkb * nnb;
;     for (int it = gw; it < items; it += ngw) { const int kb = it / nnb, nb = it - kb * nnb, n0 = nb * 32;
;         const int drow0 = rowmode ? ((n0 >> 7) * 256 + (n0 & 127) + drow_off) : (drow_off + n0);
;         tr_item(W, Ksrc, N, kb * 64, n0, dst, ldt, drow0, dcol0, scr, lane, nscale, kscale); }
.LBB0_139:
	v_mul_f32_e32 v0, v0, v167
	v_mul_f32_e32 v1, v1, v167
	v_cndmask_b32_e32 v0, 0, v0, vcc
	v_cndmask_b32_e32 v1, 0, v1, vcc
	v_add_u32_e32 v7, 0x840, v8
	ds_write2_b32 v7, v0, v1 offset1:1
	v_mul_f32_e32 v0, v2, v167
	v_mul_f32_e32 v1, v3, v167
	v_cndmask_b32_e32 v0, 0, v0, vcc
	v_cndmask_b32_e32 v1, 0, v1, vcc
	v_add_u32_e32 v2, 0x848, v8
	ds_write2_b32 v2, v0, v1 offset1:1
	s_waitcnt lgkmcnt(0)
	ds_read_b32 v0, v70
	ds_read_b32 v1, v70 offset:132
	ds_read_b32 v2, v70 offset:264
	ds_read_b32 v3, v70 offset:396
	ds_read_b32 v6, v70 offset:528
	ds_read_b32 v7, v70 offset:660
	ds_read_b32 v8, v70 offset:792
	ds_read_b32 v9, v70 offset:924
	s_waitcnt lgkmcnt(6)
	v_cvt_pk_bf16_f32 v0, v0, v1
	s_waitcnt lgkmcnt(4)
	v_cvt_pk_bf16_f32 v1, v2, v3
	s_waitcnt lgkmcnt(2)
	v_cvt_pk_bf16_f32 v2, v6, v7
	v_add_u32_e32 v6, s80, v32
	v_ashrrev_i32_e32 v7, 31, v6
	v_lshl_add_u64 v[4:5], v[4:5], 1, v[54:55]
	s_waitcnt lgkmcnt(0)
	v_cvt_pk_bf16_f32 v3, v8, v9
	v_lshlrev_b64 v[8:9], 12, v[6:7]
	v_lshl_add_u64 v[8:9], v[4:5], 0, v[8:9]
	global_store_dwordx4 v[8:9], v[0:3], off
	ds_read_b32 v0, v70 offset:32
	ds_read_b32 v1, v70 offset:164
	ds_read_b32 v2, v70 offset:296
	ds_read_b32 v3, v70 offset:428
	ds_read_b32 v7, v70 offset:560
	ds_read_b32 v8, v70 offset:692
	ds_read_b32 v9, v70 offset:824
	ds_read_b32 v10, v70 offset:956
	s_waitcnt lgkmcnt(0)
	v_cvt_pk_bf16_f32 v0, v0, v1
	v_cvt_pk_bf16_f32 v1, v2, v3
	v_cvt_pk_bf16_f32 v2, v7, v8
	v_add_u32_e32 v8, 8, v6
	v_cvt_pk_bf16_f32 v3, v9, v10
	v_ashrrev_i32_e32 v9, 31, v8
	v_lshlrev_b64 v[8:9], 12, v[8:9]
	v_lshl_add_u64 v[8:9], v[4:5], 0, v[8:9]
	global_store_dwordx4 v[8:9], v[0:3], off
	ds_read_b32 v0, v70 offset:64
	ds_read_b32 v1, v70 offset:196
	ds_read_b32 v2, v70 offset:328
	ds_read_b32 v3, v70 offset:460
	ds_read_b32 v7, v70 offset:592
	ds_read_b32 v8, v70 offset:724
	ds_read_b32 v9, v70 offset:856
	ds_read_b32 v10, v70 offset:988
	s_waitcnt lgkmcnt(0)
	v_cvt_pk_bf16_f32 v0, v0, v1
	v_cvt_pk_bf16_f32 v1, v2, v3
	v_cvt_pk_bf16_f32 v2, v7, v8
	v_add_u32_e32 v8, 16, v6
	v_cvt_pk_bf16_f32 v3, v9, v10
	v_ashrrev_i32_e32 v9, 31, v8
	v_lshlrev_b64 v[8:9], 12, v[8:9]
	v_lshl_add_u64 v[8:9], v[4:5], 0, v[8:9]
	global_store_dwordx4 v[8:9], v[0:3], off
	ds_read_b32 v0, v70 offset:96
	ds_read_b32 v1, v70 offset:228
	ds_read_b32 v2, v70 offset:360
	ds_read_b32 v3, v70 offset:492
	ds_read_b32 v7, v70 offset:624
	ds_read_b32 v8, v70 offset:756
	ds_read_b32 v9, v70 offset:888
	ds_read_b32 v10, v70 offset:1020
	v_add_u32_e32 v6, 24, v6
	s_waitcnt lgkmcnt(0)
	v_cvt_pk_bf16_f32 v0, v0, v1
	v_cvt_pk_bf16_f32 v1, v2, v3
	v_cvt_pk_bf16_f32 v2, v7, v8
	v_ashrrev_i32_e32 v7, 31, v6
	v_lshlrev_b64 v[6:7], 12, v[6:7]
	v_cvt_pk_bf16_f32 v3, v9, v10
	v_lshl_add_u64 v[4:5], v[4:5], 0, v[6:7]
	global_store_dwordx4 v[4:5], v[0:3], off
	s_waitcnt lgkmcnt(0)
	s_add_i32 s4, s4, s16
	s_add_i32 s2, s2, s27
	s_cmpk_lt_i32 s4, 0x1920
	s_cbranch_scc0 .LBB0_158
.LBB0_140:
	s_mul_hi_i32 s0, s4, 0x28c1979
	s_lshr_b32 s1, s0, 31
	s_ashr_i32 s0, s0, 1
	s_add_i32 s0, s0, s1
	s_mul_i32 s1, s0, 0xffffe6e0
	s_lshl_b32 s82, s0, 6
	s_add_i32 s80, s2, s1
	v_or_b32_e32 v56, s82, v32
	s_ashr_i32 s81, s80, 31
	v_or_b32_e32 v4, 8, v56
	v_lshl_add_u64 v[0:1], s[80:81], 2, v[52:53]
	v_min_i32_e32 v2, 0x7ff, v56
	v_min_i32_e32 v4, 0x7ff, v4
	v_mad_i64_i32 v[2:3], s[0:1], v2, s70, v[0:1]
	v_mad_i64_i32 v[4:5], s[0:1], v4, s70, v[0:1]
	global_load_dwordx4 v[28:31], v[2:3], off nt
	global_load_dwordx4 v[24:27], v[4:5], off nt
	v_or_b32_e32 v2, 16, v56
	v_or_b32_e32 v4, 24, v56
	v_min_i32_e32 v2, 0x7ff, v2
	v_min_i32_e32 v4, 0x7ff, v4
	v_mad_i64_i32 v[2:3], s[0:1], v2, s70, v[0:1]
	v_mad_i64_i32 v[4:5], s[0:1], v4, s70, v[0:1]
	global_load_dwordx4 v[20:23], v[2:3], off nt
	global_load_dwordx4 v[16:19], v[4:5], off nt
	v_or_b32_e32 v2, 32, v56
	v_or_b32_e32 v4, 40, v56
	v_min_i32_e32 v2, 0x7ff, v2
	v_min_i32_e32 v4, 0x7ff, v4
	v_mad_i64_i32 v[2:3], s[0:1], v2, s70, v[0:1]
	v_mad_i64_i32 v[4:5], s[0:1], v4, s70, v[0:1]
	global_load_dwordx4 v[12:15], v[2:3], off nt
	global_load_dwordx4 v[8:11], v[4:5], off nt
	v_or_b32_e32 v2, 48, v56
	v_or_b32_e32 v4, 56, v56
	v_min_i32_e32 v2, 0x7ff, v2
	v_min_i32_e32 v4, 0x7ff, v4
	v_mad_i64_i32 v[2:3], s[0:1], v2, s70, v[0:1]
	v_mad_i64_i32 v[0:1], s[0:1], v4, s70, v[0:1]
	global_load_dwordx4 v[4:7], v[2:3], off nt
	s_nop 0
	global_load_dwordx4 v[0:3], v[0:1], off nt
	v_cmp_gt_i32_e32 vcc, s61, v56
	s_and_b64 s[6:7], s[74:75], vcc
	v_mov_b32_e32 v71, 1.0
	v_mov_b32_e32 v57, 1.0
	v_mov_b32_e32 v161, 1.0
	v_mov_b32_e32 v162, 1.0
	v_mov_b32_e32 v163, 1.0
	v_mov_b32_e32 v164, 1.0
	v_mov_b32_e32 v165, 1.0
	v_mov_b32_e32 v166, 1.0
	v_mov_b32_e32 v167, 1.0
	s_and_saveexec_b64 s[0:1], s[6:7]
	s_cbranch_execz .LBB0_142
	v_ashrrev_i32_e32 v57, 31, v56
	v_lshl_add_u64 v[56:57], v[56:57], 2, s[40:41]
	global_load_dword v161, v[56:57], off offset:32
	global_load_dword v162, v[56:57], off offset:64
	global_load_dword v163, v[56:57], off offset:96
	global_load_dword v164, v[56:57], off offset:128
	global_load_dword v165, v[56:57], off offset:160
	global_load_dword v166, v[56:57], off offset:192
	global_load_dword v167, v[56:57], off offset:224
	global_load_dword v57, v[56:57], off
; #define LAS __attribute__((address_space(3)))
; __device__ __forceinline__ void tr_item(const float* W, int Ksrc, int N, int k0, int n0, bf16* dst, int ldt, int drow0, int dcol0, LAS float* scr, int lane, const float* nscale = nullptr, const float* kscale = nullptr) {
;     ...
;     for (int i = 0; i < 8; ++i) { const int kk = 8 * i + kr_; const int kr = (k0 + kk < Ksrc) ? (k0 + kk) : (Ksrc - 1); tv[i] = __builtin_nontemporal_load((const f32x4*)(W + (size_t)kr * N + n0 + 4 * nq_)); }
; #pragma unroll
;     for (int i = 0; i < 8; ++i) { const int kk = 8 * i + kr_; const bool ok = (k0 + kk < Ksrc); LAS float* d_ = scr + kk * 33 + 4 * nq_;
;         const float ks_ = (ok && kscale) ? kscale[k0 + kk] : 1.0f;
;         d_[0] = ok ? tv[i].x * ks_ : 0.f; d_[1] = ok ? tv[i].y * ks_ : 0.f; d_[2] = ok ? tv[i].z * ks_ : 0.f; d_[3] = ok ? tv[i].w * ks_ : 0.f; }
.LBB0_142:
	s_or_b64 exec, exec, s[0:1]
	s_waitcnt vmcnt(0) lgkmcnt(0)
	v_mul_f32_e32 v28, v28, v57
	v_mul_f32_e32 v29, v29, v57
	v_cndmask_b32_e32 v28, 0, v28, vcc
	v_cndmask_b32_e32 v29, 0, v29, vcc
	v_add_u32_e32 v56, v35, v37
	ds_write2_b32 v56, v28, v29 offset1:1
	v_mul_f32_e32 v28, v30, v57
	v_mul_f32_e32 v29, v31, v57
	v_cndmask_b32_e32 v28, 0, v28, vcc
	v_cndmask_b32_e32 v29, 0, v29, vcc
	ds_write2_b32 v56, v28, v29 offset0:2 offset1:3
	v_or_b32_e32 v28, s82, v58
	v_cmp_gt_i32_e32 vcc, s61, v28
	s_and_b64 s[6:7], s[74:75], vcc
	v_mul_f32_e32 v24, v24, v161
	v_mul_f32_e32 v25, v25, v161
	v_cndmask_b32_e32 v24, 0, v24, vcc
	v_cndmask_b32_e32 v25, 0, v25, vcc
	v_add_u32_e32 v28, v35, v59
	ds_write2_b32 v28, v24, v25 offset1:1
	v_mul_f32_e32 v24, v26, v161
	v_mul_f32_e32 v25, v27, v161
	v_cndmask_b32_e32 v24, 0, v24, vcc
	v_cndmask_b32_e32 v25, 0, v25, vcc
	ds_write2_b32 v28, v24, v25 offset0:2 offset1:3
	v_or_b32_e32 v24, s82, v60
	v_cmp_gt_i32_e32 vcc, s61, v24
	s_and_b64 s[6:7], s[74:75], vcc
	v_mov_b32_e32 v24, 1.0
	v_mov_b32_e32 v25, 1.0
	v_mul_f32_e32 v20, v20, v162
	v_mul_f32_e32 v21, v21, v162
	v_cndmask_b32_e32 v20, 0, v20, vcc
	v_cndmask_b32_e32 v21, 0, v21, vcc
	v_add_u32_e32 v26, v35, v61
	ds_write2_b32 v26, v20, v21 offset1:1
	v_mul_f32_e32 v20, v22, v162
	v_mul_f32_e32 v21, v23, v162
	v_cndmask_b32_e32 v20, 0, v20, vcc
	v_cndmask_b32_e32 v21, 0, v21, vcc
	ds_write2_b32 v26, v20, v21 offset0:2 offset1:3
	v_or_b32_e32 v20, s82, v62
	v_cmp_gt_i32_e32 vcc, s61, v20
	s_and_b64 s[6:7], s[74:75], vcc
	v_mul_f32_e32 v16, v16, v163
	v_mul_f32_e32 v17, v17, v163
	v_cndmask_b32_e32 v16, 0, v16, vcc
	v_cndmask_b32_e32 v17, 0, v17, vcc
	v_add_u32_e32 v20, v35, v63
	ds_write2_b32 v20, v16, v17 offset1:1
	v_mul_f32_e32 v16, v18, v163
	v_mul_f32_e32 v17, v19, v163
	v_cndmask_b32_e32 v16, 0, v16, vcc
	v_cndmask_b32_e32 v17, 0, v17, vcc
	ds_write2_b32 v20, v16, v17 offset0:2 offset1:3
	v_or_b32_e32 v16, s82, v64
	v_cmp_gt_i32_e32 vcc, s61, v16
	s_and_b64 s[6:7], s[74:75], vcc
	v_mov_b32_e32 v16, 1.0
	v_mov_b32_e32 v17, 1.0
	v_mul_f32_e32 v12, v12, v164
	v_mul_f32_e32 v13, v13, v164
	v_cndmask_b32_e32 v12, 0, v12, vcc
	v_cndmask_b32_e32 v13, 0, v13, vcc
	v_add_u32_e32 v18, v35, v65
	ds_write2_b32 v18, v12, v13 offset1:1
	v_mul_f32_e32 v12, v14, v164
	v_mul_f32_e32 v13, v15, v164
	v_cndmask_b32_e32 v12, 0, v12, vcc
	v_cndmask_b32_e32 v13, 0, v13, vcc
	ds_write2_b32 v18, v12, v13 offset0:2 offset1:3
	v_or_b32_e32 v12, s82, v66
	v_cmp_gt_i32_e32 vcc, s61, v12
	s_and_b64 s[6:7], s[74:75], vcc
	v_mul_f32_e32 v8, v8, v165
	v_mul_f32_e32 v9, v9, v165
	v_cndmask_b32_e32 v12, 0, v8, vcc
	v_cndmask_b32_e32 v9, 0, v9, vcc
	v_add_u32_e32 v8, v35, v67
	ds_write2_b32 v8, v12, v9 offset1:1
	v_mul_f32_e32 v9, v10, v165
	v_mul_f32_e32 v10, v11, v165
	v_cndmask_b32_e32 v9, 0, v9, vcc
	v_cndmask_b32_e32 v10, 0, v10, vcc
	ds_write2_b32 v8, v9, v10 offset0:2 offset1:3
	v_or_b32_e32 v9, s82, v68
	v_cmp_gt_i32_e32 vcc, s61, v9
	s_and_b64 s[6:7], s[74:75], vcc
	v_mov_b32_e32 v9, 1.0
	v_mul_f32_e32 v4, v4, v166
	v_mul_f32_e32 v5, v5, v166
	v_cndmask_b32_e32 v4, 0, v4, vcc
	v_cndmask_b32_e32 v5, 0, v5, vcc
	v_add_u32_e32 v10, 0x420, v8
	ds_write2_b32 v10, v4, v5 offset1:1
	v_mul_f32_e32 v4, v6, v166
	v_mul_f32_e32 v5, v7, v166
	v_cndmask_b32_e32 v4, 0, v4, vcc
	v_cndmask_b32_e32 v5, 0, v5, vcc
	v_add_u32_e32 v6, 0x428, v8
	ds_write2_b32 v6, v4, v5 offset1:1
	v_or_b32_e32 v4, s82, v69
	v_cmp_gt_i32_e32 vcc, s61, v4
	s_ashr_i32 s83, s82, 31
	v_mov_b64_e32 v[4:5], s[82:83]
	s_branch .LBB0_139

; __device__ __forceinline__ unsigned pk_bf16(float lo, float hi) { f32x2e v = {lo, hi}; bf16x2e b = __builtin_convertvector(v, bf16x2e); return __builtin_bit_cast(unsigned, b); }
; #define LAS __attribute__((address_space(3)))
; __device__ __forceinline__ void tr_item(const float* W, int Ksrc, int N, int k0, int n0, bf16* dst, int ldt, int drow0, int dcol0, LAS float* scr, int lane, const float* nscale = nullptr, const float* kscale = nullptr) {
;     ...
;     for (int i = 0; i < 8; ++i) { const int kk = 8 * i + kr_; const int kr = (k0 + kk < Ksrc) ? (k0 + kk) : (Ksrc - 1); tv[i] = __builtin_nontemporal_load((const f32x4*)(W + (size_t)kr * N + n0 + 4 * nq_)); }
;     ...
;     asm volatile("s_waitcnt lgkmcnt(0)" ::: "memory");
;     const int c = lane & 7;
; #pragma unroll
;     for (int j = 0; j < 4; ++j) { const int n = (lane >> 3) + 8 * j; const LAS float* s = scr + (8 * c) * 33 + n;
;         const float sc = nscale ? nscale[n0 + n] : 1.0f;
;         u32x4 o; o.x = pk_bf16(s[0 * 33] * sc, s[1 * 33] * sc); o.y = pk_bf16(s[2 * 33] * sc, s[3 * 33] * sc); o.z = pk_bf16(s[4 * 33] * sc, s[5 * 33] * sc); o.w = pk_bf16(s[6 * 33] * sc, s[7 * 33] * sc);
;         *(u32x4*)(dst + (size_t)(drow0 + n) * ldt + dcol0 + k0 + 8 * c) = o; }
;     asm volatile("s_waitcnt lgkmcnt(0)" ::: "memory");
; __device__ __forceinline__ void tr_matrix(const float* W, int Ksrc, int N, bf16* dst, int ldt, int dcol0, int rowmode, int drow_off, LAS float* scr, int gw, int ngw, int lane, const float* nscale = nullptr, const float* kscale = nullptr) {
;     ...
;     for (int it = gw; it < items; it += ngw) { const int kb = it / nnb, nb = it - kb * nnb, n0 = nb * 32;
;         const int drow0 = rowmode ? ((n0 >> 7) * 256 + (n0 & 127) + drow_off) : (drow_off + n0);
;         tr_item(W, Ksrc, N, kb * 64, n0, dst, ldt, drow0, dcol0, scr, lane, nscale, kscale); }
.LBB0_172:
	v_mul_f32_e32 v0, v0, v167
	v_mul_f32_e32 v1, v1, v167
	v_cndmask_b32_e32 v0, 0, v0, vcc
	v_cndmask_b32_e32 v1, 0, v1, vcc
	v_add_u32_e32 v7, 0x840, v8
	ds_write2_b32 v7, v0, v1 offset1:1
	v_mul_f32_e32 v0, v2, v167
	v_mul_f32_e32 v1, v3, v167
	v_cndmask_b32_e32 v0, 0, v0, vcc
	v_cndmask_b32_e32 v1, 0, v1, vcc
	v_add_u32_e32 v2, 0x848, v8
	ds_write2_b32 v2, v0, v1 offset1:1
	s_waitcnt lgkmcnt(0)
	ds_read_b32 v0, v70
	ds_read_b32 v1, v70 offset:132
	ds_read_b32 v2, v70 offset:264
	ds_read_b32 v3, v70 offset:396
	ds_read_b32 v6, v70 offset:528
	ds_read_b32 v7, v70 offset:660
	ds_read_b32 v8, v70 offset:792
	ds_read_b32 v9, v70 offset:924
	s_waitcnt lgkmcnt(6)
	v_cvt_pk_bf16_f32 v0, v0, v1
	s_waitcnt lgkmcnt(4)
	v_cvt_pk_bf16_f32 v1, v2, v3
	s_waitcnt lgkmcnt(2)
	v_cvt_pk_bf16_f32 v2, v6, v7
	v_add_u32_e32 v6, s94, v32
	v_ashrrev_i32_e32 v7, 31, v6
	v_lshl_add_u64 v[4:5], v[4:5], 1, v[54:55]
	s_waitcnt lgkmcnt(0)
	v_cvt_pk_bf16_f32 v3, v8, v9
	v_lshlrev_b64 v[8:9], 12, v[6:7]
	v_lshl_add_u64 v[8:9], v[4:5], 0, v[8:9]
	global_store_dwordx4 v[8:9], v[0:3], off
	ds_read_b32 v0, v70 offset:32
	ds_read_b32 v1, v70 offset:164
	ds_read_b32 v2, v70 offset:296
	ds_read_b32 v3, v70 offset:428
	ds_read_b32 v7, v70 offset:560
	ds_read_b32 v8, v70 offset:692
	ds_read_b32 v9, v70 offset:824
	ds_read_b32 v10, v70 offset:956
	s_waitcnt lgkmcnt(0)
	v_cvt_pk_bf16_f32 v0, v0, v1
	v_cvt_pk_bf16_f32 v1, v2, v3
	v_cvt_pk_bf16_f32 v2, v7, v8
	v_add_u32_e32 v8, 8, v6
	v_cvt_pk_bf16_f32 v3, v9, v10
	v_ashrrev_i32_e32 v9, 31, v8
	v_lshlrev_b64 v[8:9], 12, v[8:9]
	v_lshl_add_u64 v[8:9], v[4:5], 0, v[8:9]
	global_store_dwordx4 v[8:9], v[0:3], off
	ds_read_b32 v0, v70 offset:64
	ds_read_b32 v1, v70 offset:196
	ds_read_b32 v2, v70 offset:328
	ds_read_b32 v3, v70 offset:460
	ds_read_b32 v7, v70 offset:592
	ds_read_b32 v8, v70 offset:724
	ds_read_b32 v9, v70 offset:856
	ds_read_b32 v10, v70 offset:988
	s_waitcnt lgkmcnt(0)
	v_cvt_pk_bf16_f32 v0, v0, v1
	v_cvt_pk_bf16_f32 v1, v2, v3
	v_cvt_pk_bf16_f32 v2, v7, v8
	v_add_u32_e32 v8, 16, v6
	v_cvt_pk_bf16_f32 v3, v9, v10
	v_ashrrev_i32_e32 v9, 31, v8
	v_lshlrev_b64 v[8:9], 12, v[8:9]
	v_lshl_add_u64 v[8:9], v[4:5], 0, v[8:9]
	global_store_dwordx4 v[8:9], v[0:3], off
	ds_read_b32 v0, v70 offset:96
	ds_read_b32 v1, v70 offset:228
	ds_read_b32 v2, v70 offset:360
	ds_read_b32 v3, v70 offset:492
	ds_read_b32 v7, v70 offset:624
	ds_read_b32 v8, v70 offset:756
	ds_read_b32 v9, v70 offset:888
	ds_read_b32 v10, v70 offset:1020
	v_add_u32_e32 v6, 24, v6
	s_waitcnt lgkmcnt(0)
	v_cvt_pk_bf16_f32 v0, v0, v1
	v_cvt_pk_bf16_f32 v1, v2, v3
	v_cvt_pk_bf16_f32 v2, v7, v8
	v_ashrrev_i32_e32 v7, 31, v6
	v_lshlrev_b64 v[6:7], 12, v[6:7]
	v_cvt_pk_bf16_f32 v3, v9, v10
	v_lshl_add_u64 v[4:5], v[4:5], 0, v[6:7]
	global_store_dwordx4 v[4:5], v[0:3], off
	s_waitcnt lgkmcnt(0)
	s_add_i32 s4, s4, s16
	s_add_i32 s2, s2, s27
	s_cmpk_lt_i32 s4, 0x640
	s_cbranch_scc0 .LBB0_191
.LBB0_173:
	s_mul_hi_i32 s0, s4, 0x51eb851f
	s_lshr_b32 s1, s0, 31
	s_ashr_i32 s0, s0, 4
	s_add_i32 s0, s0, s1
	s_mul_i32 s1, s0, 0xfffff9c0
	s_lshl_b32 s96, s0, 6
	s_add_i32 s94, s2, s1
	v_or_b32_e32 v56, s96, v32
	s_ashr_i32 s95, s94, 31
	v_or_b32_e32 v4, 8, v56
	v_lshl_add_u64 v[0:1], s[94:95], 2, v[52:53]
	v_min_i32_e32 v2, 0x7ff, v56
	v_min_i32_e32 v4, 0x7ff, v4
	v_mad_i64_i32 v[2:3], s[0:1], v2, s50, v[0:1]
	v_mad_i64_i32 v[4:5], s[0:1], v4, s50, v[0:1]
	global_load_dwordx4 v[28:31], v[2:3], off nt
	global_load_dwordx4 v[24:27], v[4:5], off nt
	v_or_b32_e32 v2, 16, v56
	v_or_b32_e32 v4, 24, v56
	v_min_i32_e32 v2, 0x7ff, v2
	v_min_i32_e32 v4, 0x7ff, v4
	v_mad_i64_i32 v[2:3], s[0:1], v2, s50, v[0:1]
	v_mad_i64_i32 v[4:5], s[0:1], v4, s50, v[0:1]
	global_load_dwordx4 v[20:23], v[2:3], off nt
	global_load_dwordx4 v[16:19], v[4:5], off nt
	v_or_b32_e32 v2, 32, v56
	v_or_b32_e32 v4, 40, v56
	v_min_i32_e32 v2, 0x7ff, v2
	v_min_i32_e32 v4, 0x7ff, v4
	v_mad_i64_i32 v[2:3], s[0:1], v2, s50, v[0:1]
	v_mad_i64_i32 v[4:5], s[0:1], v4, s50, v[0:1]
	global_load_dwordx4 v[12:15], v[2:3], off nt
	global_load_dwordx4 v[8:11], v[4:5], off nt
	v_or_b32_e32 v2, 48, v56
	v_or_b32_e32 v4, 56, v56
	v_min_i32_e32 v2, 0x7ff, v2
	v_min_i32_e32 v4, 0x7ff, v4
	v_mad_i64_i32 v[2:3], s[0:1], v2, s50, v[0:1]
	v_mad_i64_i32 v[0:1], s[0:1], v4, s50, v[0:1]
	global_load_dwordx4 v[4:7], v[2:3], off nt
	s_nop 0
	global_load_dwordx4 v[0:3], v[0:1], off nt
	v_cmp_gt_i32_e32 vcc, s61, v56
	s_and_b64 s[6:7], s[86:87], vcc
	v_mov_b32_e32 v71, 1.0
	v_mov_b32_e32 v57, 1.0
	v_mov_b32_e32 v161, 1.0
	v_mov_b32_e32 v162, 1.0
	v_mov_b32_e32 v163, 1.0
	v_mov_b32_e32 v164, 1.0
	v_mov_b32_e32 v165, 1.0
	v_mov_b32_e32 v166, 1.0
	v_mov_b32_e32 v167, 1.0
	s_and_saveexec_b64 s[0:1], s[6:7]
	s_cbranch_execz .LBB0_175
	v_ashrrev_i32_e32 v57, 31, v56
	v_lshl_add_u64 v[56:57], v[56:57], 2, s[40:41]
	global_load_dword v161, v[56:57], off offset:32
	global_load_dword v162, v[56:57], off offset:64
	global_load_dword v163, v[56:57], off offset:96
	global_load_dword v164, v[56:57], off offset:128
	global_load_dword v165, v[56:57], off offset:160
	global_load_dword v166, v[56:57], off offset:192
	global_load_dword v167, v[56:57], off offset:224
	global_load_dword v57, v[56:57], off
; #define LAS __attribute__((address_space(3)))
; __device__ __forceinline__ void tr_item(const float* W, int Ksrc, int N, int k0, int n0, bf16* dst, int ldt, int drow0, int dcol0, LAS float* scr, int lane, const float* nscale = nullptr, const float* kscale = nullptr) {
;     ...
;     for (int i = 0; i < 8; ++i) { const int kk = 8 * i + kr_; const int kr = (k0 + kk < Ksrc) ? (k0 + kk) : (Ksrc - 1); tv[i] = __builtin_nontemporal_load((const f32x4*)(W + (size_t)kr * N + n0 + 4 * nq_)); }
; #pragma unroll
;     for (int i = 0; i < 8; ++i) { const int kk = 8 * i + kr_; const bool ok = (k0 + kk < Ksrc); LAS float* d_ = scr + kk * 33 + 4 * nq_;
;         const float ks_ = (ok && kscale) ? kscale[k0 + kk] : 1.0f;
;         d_[0] = ok ? tv[i].x * ks_ : 0.f; d_[1] = ok ? tv[i].y * ks_ : 0.f; d_[2] = ok ? tv[i].z * ks_ : 0.f; d_[3] = ok ? tv[i].w * ks_ : 0.f; }
.LBB0_175:
	s_or_b64 exec, exec, s[0:1]
	s_waitcnt vmcnt(0) lgkmcnt(0)
	v_mul_f32_e32 v28, v28, v57
	v_mul_f32_e32 v29, v29, v57
	v_cndmask_b32_e32 v28, 0, v28, vcc
	v_cndmask_b32_e32 v29, 0, v29, vcc
	v_add_u32_e32 v56, v35, v37
	ds_write2_b32 v56, v28, v29 offset1:1
	v_mul_f32_e32 v28, v30, v57
	v_mul_f32_e32 v29, v31, v57
	v_cndmask_b32_e32 v28, 0, v28, vcc
	v_cndmask_b32_e32 v29, 0, v29, vcc
	ds_write2_b32 v56, v28, v29 offset0:2 offset1:3
	v_or_b32_e32 v28, s96, v58
	v_cmp_gt_i32_e32 vcc, s61, v28
	s_and_b64 s[6:7], s[86:87], vcc
	v_mul_f32_e32 v24, v24, v161
	v_mul_f32_e32 v25, v25, v161
	v_cndmask_b32_e32 v24, 0, v24, vcc
	v_cndmask_b32_e32 v25, 0, v25, vcc
	v_add_u32_e32 v28, v35, v59
	ds_write2_b32 v28, v24, v25 offset1:1
	v_mul_f32_e32 v24, v26, v161
	v_mul_f32_e32 v25, v27, v161
	v_cndmask_b32_e32 v24, 0, v24, vcc
	v_cndmask_b32_e32 v25, 0, v25, vcc
	ds_write2_b32 v28, v24, v25 offset0:2 offset1:3
	v_or_b32_e32 v24, s96, v60
	v_cmp_gt_i32_e32 vcc, s61, v24
	s_and_b64 s[6:7], s[86:87], vcc
	v_mov_b32_e32 v24, 1.0
	v_mov_b32_e32 v25, 1.0
	v_mul_f32_e32 v20, v20, v162
	v_mul_f32_e32 v21, v21, v162
	v_cndmask_b32_e32 v20, 0, v20, vcc
	v_cndmask_b32_e32 v21, 0, v21, vcc
	v_add_u32_e32 v26, v35, v61
	ds_write2_b32 v26, v20, v21 offset1:1
	v_mul_f32_e32 v20, v22, v162
	v_mul_f32_e32 v21, v23, v162
	v_cndmask_b32_e32 v20, 0, v20, vcc
	v_cndmask_b32_e32 v21, 0, v21, vcc
	ds_write2_b32 v26, v20, v21 offset0:2 offset1:3
	v_or_b32_e32 v20, s96, v62
	v_cmp_gt_i32_e32 vcc, s61, v20
	s_and_b64 s[6:7], s[86:87], vcc
	v_mul_f32_e32 v16, v16, v163
	v_mul_f32_e32 v17, v17, v163
	v_cndmask_b32_e32 v16, 0, v16, vcc
	v_cndmask_b32_e32 v17, 0, v17, vcc
	v_add_u32_e32 v20, v35, v63
	ds_write2_b32 v20, v16, v17 offset1:1
	v_mul_f32_e32 v16, v18, v163
	v_mul_f32_e32 v17, v19, v163
	v_cndmask_b32_e32 v16, 0, v16, vcc
	v_cndmask_b32_e32 v17, 0, v17, vcc
	ds_write2_b32 v20, v16, v17 offset0:2 offset1:3
	v_or_b32_e32 v16, s96, v64
	v_cmp_gt_i32_e32 vcc, s61, v16
	s_and_b64 s[6:7], s[86:87], vcc
	v_mov_b32_e32 v16, 1.0
	v_mov_b32_e32 v17, 1.0
	v_mul_f32_e32 v12, v12, v164
	v_mul_f32_e32 v13, v13, v164
	v_cndmask_b32_e32 v12, 0, v12, vcc
	v_cndmask_b32_e32 v13, 0, v13, vcc
	v_add_u32_e32 v18, v35, v65
	ds_write2_b32 v18, v12, v13 offset1:1
	v_mul_f32_e32 v12, v14, v164
	v_mul_f32_e32 v13, v15, v164
	v_cndmask_b32_e32 v12, 0, v12, vcc
	v_cndmask_b32_e32 v13, 0, v13, vcc
	ds_write2_b32 v18, v12, v13 offset0:2 offset1:3
	v_or_b32_e32 v12, s96, v66
	v_cmp_gt_i32_e32 vcc, s61, v12
	s_and_b64 s[6:7], s[86:87], vcc
	v_mul_f32_e32 v8, v8, v165
	v_mul_f32_e32 v9, v9, v165
	v_cndmask_b32_e32 v12, 0, v8, vcc
	v_cndmask_b32_e32 v9, 0, v9, vcc
	v_add_u32_e32 v8, v35, v67
	ds_write2_b32 v8, v12, v9 offset1:1
	v_mul_f32_e32 v9, v10, v165
	v_mul_f32_e32 v10, v11, v165
	v_cndmask_b32_e32 v9, 0, v9, vcc
	v_cndmask_b32_e32 v10, 0, v10, vcc
	ds_write2_b32 v8, v9, v10 offset0:2 offset1:3
	v_or_b32_e32 v9, s96, v68
	v_cmp_gt_i32_e32 vcc, s61, v9
	s_and_b64 s[6:7], s[86:87], vcc
	v_mov_b32_e32 v9, 1.0
	v_mul_f32_e32 v4, v4, v166
	v_mul_f32_e32 v5, v5, v166
	v_cndmask_b32_e32 v4, 0, v4, vcc
	v_cndmask_b32_e32 v5, 0, v5, vcc
	v_add_u32_e32 v10, 0x420, v8
	ds_write2_b32 v10, v4, v5 offset1:1
	v_mul_f32_e32 v4, v6, v166
	v_mul_f32_e32 v5, v7, v166
	v_cndmask_b32_e32 v4, 0, v4, vcc
	v_cndmask_b32_e32 v5, 0, v5, vcc
	v_add_u32_e32 v6, 0x428, v8
	ds_write2_b32 v6, v4, v5 offset1:1
	v_or_b32_e32 v4, s96, v69
	v_cmp_gt_i32_e32 vcc, s61, v4
	s_ashr_i32 s97, s96, 31
	v_mov_b64_e32 v[4:5], s[96:97]
	s_branch .LBB0_172
